# post-grid-sync team XCC-id check: the 4 serialized sc1 loads (one wait each, early-exit branches) issued together with a single wait and a branch-free compare; on top of v029
# baseline (speedup 1.0000x reference)
; __device__ __forceinline__ unsigned xb_ld(unsigned* p)              { return __hip_atomic_load(p, __ATOMIC_RELAXED, __HIP_MEMORY_SCOPE_AGENT); }
; __device__ __forceinline__ unsigned xb_xcc_id() { return (unsigned)__builtin_amdgcn_s_getreg((3 << 11) | 20) & 0xFu; }
; __global__ void __launch_bounds__(512, 2) mega_fwd(Args a) {
;     ...
;             if (threadIdx.x == 0) { const unsigned me = xb_xcc_id() + 1u; bool sm = true;
; #pragma unroll
;                 for (int j = 0; j < 4; ++j) sm = sm && (xb_ld(barw + 8192 + (blockIdx.x & 63) + 64 * j) == me);
;                 MISC[12] = sm ? 1u : 0u; }
;             __syncthreads();
;             T.on = true; T.same = MISC[12] != 0u; } }
.LBB0_345:
	s_or_b64 exec, exec, s[0:1]
	s_cmpk_eq_i32 s12, 0x100
	v_readlane_b32 s10, v254, 0
	s_cselect_b64 s[0:1], -1, 0
	s_cmp_eq_u32 s10, 0
	s_cselect_b64 s[4:5], -1, 0
	v_readlane_b32 s11, v254, 1
	s_and_b64 s[0:1], s[0:1], s[4:5]
	s_cmp_eq_u32 s11, 18
	s_cselect_b64 s[4:5], -1, 0
	s_and_b64 s[0:1], s[0:1], s[4:5]
	s_mov_b64 s[10:11], 0
	s_andn2_b64 vcc, exec, s[0:1]
	s_mov_b64 s[88:89], 0
	s_cbranch_vccnz .LBB0_353
	s_and_saveexec_b64 s[0:1], s[6:7]
	s_cbranch_execz .LBB0_352
	s_getreg_b32 s4, hwreg(HW_REG_XCC_ID, 0, 4)
	s_and_b32 s6, s4, 15
	s_and_b32 s4, s2, 63
	s_add_i32 s6, s6, 1
	s_lshl_b32 s4, s4, 2
	s_add_u32 s4, s74, s4
	s_addc_u32 s5, s75, 0
	s_add_u32 s4, s4, 0x8000
	s_addc_u32 s5, s5, 0
	v_mov_b32_e32 v0, 0
	global_load_dword v1, v0, s[4:5] sc1
	global_load_dword v2, v0, s[4:5] offset:256 sc1
	global_load_dword v3, v0, s[4:5] offset:512 sc1
	global_load_dword v4, v0, s[4:5] offset:768 sc1
	s_waitcnt vmcnt(0)
	v_xor_b32_e32 v1, s6, v1
	v_xor_b32_e32 v2, s6, v2
	v_xor_b32_e32 v3, s6, v3
	v_xor_b32_e32 v4, s6, v4
	v_or3_b32 v1, v1, v2, v3
	v_or_b32_e32 v1, v1, v4
	v_cmp_eq_u32_e32 vcc, 0, v1
	s_nop 1
	v_cndmask_b32_e64 v0, 0, 1, vcc
